# prompt-attention K staging: the xor-1/2/4 lane exchanges as DPP moves instead of ds_bpermute (on top of v90)
# speedup vs baseline: 1.0056x; 1.0008x over previous
; template <bool SAMPLE>
; __device__ __forceinline__ void attn_prefetch(const bf16_t* __restrict__ proj, int row0, int head0, int lane, u32x4 (&qw)[4], u32x4 (&zw)[4]) {
;     const int r32 = lane & 31, hi = lane >> 5;
;     const int myrow = SAMPLE ? row0 + (r32 & 7) : row0 + r32;
;     const int myhead = SAMPLE ? head0 + (r32 >> 3) : head0;
;     const bf16_t* qp = proj + (size_t)myrow * PO2 + C_Q + myhead * 64 + hi * 8;
; #pragma unroll
;     for (int d0 = 0; d0 < 4; ++d0) qw[d0] = *(const u32x4*)(qp + d0 * 16);
; #pragma unroll
;     for (int it4 = 0; it4 < 4; ++it4) {
;         const int qq = it4 * 8 + (lane >> 3), ch = lane & 7;
;         const int orow = SAMPLE ? row0 + (qq & 7) : row0 + qq;
;         const int ohead = SAMPLE ? head0 + (qq >> 3) : head0;
;         zw[it4] = *(const u32x4*)(proj + (size_t)orow * PO2 + C_ZA + ohead * 64 + ch * 8);
;     }
; __device__ __forceinline__ void attn_prompt_item(const Args& a, int l, int item, LAS unsigned char* lds, int tid, int lane, int wave) {
;     ...
;     const int headw = kvh * 4 + (wave >> 1), qt0 = (wave & 1) * 2, rowq0 = n * LP + b * 128 + qt0 * 32;
;     u32x4 qw0[4], zw0[4], qw1[4], zw1[4];
;     attn_prefetch<false>(proj, rowq0, headw, lane, qw0, zw0); attn_prefetch<false>(proj, rowq0 + 32, headw, lane, qw1, zw1);
;     const int sub = tid & 7, rl = tid >> 3;
;     u32x4 kws[4], vws[4];
; #pragma unroll
;     for (int pass = 0; pass < 4; ++pass) {
;         const int j = pass * 64 + rl; const int pos = 128 * (b - 1) + j; const int posc = pos < 0 ? 0 : pos;
;         const size_t row = (size_t)n * LP + posc;
;         kws[pass] = *(const u32x4*)(proj + row * PO2 + C_K + kvh * 64 + sub * 8);
;         vws[pass] = *(const u32x4*)(proj + row * PO2 + C_V + kvh * 64 + sub * 8);
;     }
.LBB0_459:
	s_and_b32 s10, s71, 1
	s_bfe_u32 s7, s71, 0x50001
	s_ashr_i32 s4, s71, 6
	s_lshl_b32 s0, s10, 2
	s_add_i32 s6, s0, s45
	s_lshl_b32 s0, s4, 12
	s_lshl_b32 s12, s7, 7
	s_or_b32 s0, s12, s0
	s_or_b32 s92, s0, s33
	v_and_b32_e32 v134, 31, v131
	v_and_b32_e32 v132, 63, v131
	v_or_b32_e32 v0, s92, v134
	v_mov_b64_e32 v[16:17], s[74:75]
	v_mad_i64_i32 v[0:1], s[0:1], v0, s97, v[16:17]
	v_bfe_u32 v133, v131, 3, 3
	v_lshlrev_b32_e32 v135, 3, v132
	s_lshl_b32 s0, s6, 6
	v_or_b32_e32 v128, s92, v133
	v_and_b32_e32 v20, 56, v135
	s_ashr_i32 s1, s0, 31
	v_lshlrev_b32_e32 v124, 1, v20
	v_or_b32_e32 v20, 8, v128
	s_lshl_b64 s[52:53], s[0:1], 1
	v_lshrrev_b32_e32 v2, 1, v131
	v_mad_i64_i32 v[18:19], s[0:1], v128, s97, v[16:17]
	v_mad_i64_i32 v[20:21], s[0:1], v20, s97, v[16:17]
	v_lshl_add_u64 v[0:1], v[0:1], 0, s[52:53]
	v_and_b32_e32 v172, 16, v2
	v_lshl_add_u64 v[18:19], v[18:19], 0, s[52:53]
	v_mov_b32_e32 v125, v173
	v_lshl_add_u64 v[20:21], v[20:21], 0, s[52:53]
	s_or_b32 s73, s92, 32
	v_lshl_add_u64 v[12:13], v[0:1], 0, v[172:173]
	v_lshl_add_u64 v[18:19], v[18:19], 0, v[124:125]
	v_lshl_add_u64 v[20:21], v[20:21], 0, v[124:125]
	v_or_b32_e32 v22, s73, v132
	global_load_dwordx4 v[0:3], v[12:13], off offset:2048
	global_load_dwordx4 v[4:7], v[12:13], off offset:2080
	global_load_dwordx4 v[8:11], v[12:13], off offset:2112
	s_nop 0
	global_load_dwordx4 v[12:15], v[12:13], off offset:2144
	s_nop 0
	global_load_dwordx4 v[108:111], v[18:19], off offset:3584
	global_load_dwordx4 v[104:107], v[20:21], off offset:3584
	v_or_b32_e32 v18, 16, v128
	v_or_b32_e32 v20, 24, v128
	v_mad_i64_i32 v[22:23], s[0:1], v22, s97, v[16:17]
	v_ashrrev_i32_e32 v60, 3, v131
	s_add_i32 s13, s12, 0xffffff80
	v_mad_i64_i32 v[18:19], s[0:1], v18, s97, v[16:17]
	v_mad_i64_i32 v[20:21], s[0:1], v20, s97, v[16:17]
	v_lshl_add_u64 v[22:23], v[22:23], 0, s[52:53]
	v_add_u32_e32 v58, s13, v60
	s_ashr_i32 s5, s4, 31
	v_lshl_add_u64 v[22:23], v[22:23], 0, v[172:173]
	s_lshl_b64 s[0:1], s[4:5], 12
	v_max_i32_e32 v172, 0, v58
	v_lshl_add_u64 v[24:25], s[0:1], 0, v[172:173]
	v_mad_u64_u32 v[26:27], s[8:9], v24, s97, v[16:17]
	v_and_b32_e32 v61, 7, v131
	v_mad_i32_i24 v27, v25, s97, v27
	s_lshl_b32 s86, s10, 7
	v_lshl_add_u64 v[24:25], v[26:27], 0, s[86:87]
	v_lshlrev_b32_e32 v56, 4, v61
	v_mov_b32_e32 v57, v173
	v_lshl_add_u64 v[18:19], v[18:19], 0, s[52:53]
	v_lshl_add_u64 v[20:21], v[20:21], 0, s[52:53]
	v_lshl_add_u64 v[24:25], v[24:25], 0, v[56:57]
	v_lshl_add_u64 v[18:19], v[18:19], 0, v[124:125]
	v_lshl_add_u64 v[20:21], v[20:21], 0, v[124:125]
	global_load_dwordx4 v[52:55], v[24:25], off offset:3072
	global_load_dwordx4 v[100:103], v[18:19], off offset:3584
	global_load_dwordx4 v[96:99], v[20:21], off offset:3584
	global_load_dwordx4 v[80:83], v[22:23], off offset:2048
	global_load_dwordx4 v[84:87], v[22:23], off offset:2080
	global_load_dwordx4 v[88:91], v[22:23], off offset:2112
	global_load_dwordx4 v[92:95], v[22:23], off offset:2144
	v_or_b32_e32 v126, s73, v133
	v_mad_i64_i32 v[18:19], s[8:9], v126, s97, v[16:17]
	v_or_b32_e32 v20, 8, v126
	v_lshl_add_u64 v[18:19], v[18:19], 0, s[52:53]
	v_mad_i64_i32 v[20:21], s[8:9], v20, s97, v[16:17]
	v_lshl_add_u64 v[18:19], v[18:19], 0, v[124:125]
	v_lshl_add_u64 v[20:21], v[20:21], 0, s[52:53]
	v_lshl_add_u64 v[20:21], v[20:21], 0, v[124:125]
	global_load_dwordx4 v[76:79], v[18:19], off offset:3584
	global_load_dwordx4 v[72:75], v[20:21], off offset:3584
	v_or_b32_e32 v18, 16, v126
	v_mad_i64_i32 v[18:19], s[8:9], v18, s97, v[16:17]
	v_or_b32_e32 v20, 24, v126
	v_lshl_add_u64 v[18:19], v[18:19], 0, s[52:53]
	v_mad_i64_i32 v[20:21], s[8:9], v20, s97, v[16:17]
	v_lshl_add_u64 v[18:19], v[18:19], 0, v[124:125]
	v_lshl_add_u64 v[20:21], v[20:21], 0, s[52:53]
	v_lshl_add_u64 v[20:21], v[20:21], 0, v[124:125]
	global_load_dwordx4 v[68:71], v[18:19], off offset:3584
	global_load_dwordx4 v[64:67], v[20:21], off offset:3584
	global_load_dwordx4 v[48:51], v[24:25], off offset:3328
	v_max_i32_e32 v18, 0xffffffc0, v58
	v_add_u32_e32 v18, 64, v18
	v_mov_b32_e32 v19, v173
	v_lshl_add_u64 v[18:19], s[0:1], 0, v[18:19]
	v_mad_u64_u32 v[20:21], s[8:9], v18, s97, v[16:17]
	v_mad_i32_i24 v21, v19, s97, v21
	v_lshl_add_u64 v[18:19], v[20:21], 0, s[86:87]
	v_lshl_add_u64 v[18:19], v[18:19], 0, v[56:57]
	global_load_dwordx4 v[36:39], v[18:19], off offset:3072
	global_load_dwordx4 v[28:31], v[18:19], off offset:3328
	v_add_u32_e32 v18, s12, v60
	v_max_i32_e32 v112, 0, v18
	v_mov_b32_e32 v113, v173
	v_lshl_add_u64 v[18:19], s[0:1], 0, v[112:113]
	v_mad_u64_u32 v[20:21], s[8:9], v18, s97, v[16:17]
	v_lshlrev_b32_e32 v62, 5, v61
	v_mad_i32_i24 v21, v19, s97, v21
	global_load_dwordx4 v[40:43], v62, s[98:99] offset:16
	global_load_dwordx4 v[44:47], v62, s[98:99]
	v_lshl_add_u64 v[18:19], v[20:21], 0, s[86:87]
	v_lshl_add_u64 v[18:19], v[18:19], 0, v[56:57]
	global_load_dwordx4 v[32:35], v[18:19], off offset:3072
	global_load_dwordx4 v[24:27], v[18:19], off offset:3328
	v_max_i32_e32 v18, 0xffffff40, v58
	v_add_u32_e32 v18, 0xc0, v18
	v_mov_b32_e32 v19, v173
	v_lshl_add_u64 v[18:19], s[0:1], 0, v[18:19]
	v_mad_u64_u32 v[16:17], s[0:1], v18, s97, v[16:17]
	v_mad_i32_i24 v17, v19, s97, v17
	v_lshl_add_u64 v[16:17], v[16:17], 0, s[86:87]
	v_lshl_add_u64 v[16:17], v[16:17], 0, v[56:57]
	global_load_dwordx4 v[20:23], v[16:17], off offset:3072
	s_nop 0
	global_load_dwordx4 v[16:19], v[16:17], off offset:3328
	v_cmp_lt_i32_e32 vcc, v215, v214
	v_cmp_gt_u32_e64 s[0:1], 2, v61
	s_waitcnt vmcnt(19)
; __device__ __forceinline__ void normrope8(float (&v)[8], int sub, const float* gain, const float* tabrow) {
;     float ss = 0.f;
; #pragma unroll
;     for (int i = 0; i < 8; ++i) ss += v[i] * v[i];
;     ss += __shfl_xor(ss, 1); ss += __shfl_xor(ss, 2); ss += __shfl_xor(ss, 4);
;     const float rstd = rsqrtf(ss * (1.0f / 64.0f) + EPS);
;     const f32x4 g0 = *(const f32x4*)(gain + sub * 8), g1 = *(const f32x4*)(gain + sub * 8 + 4);
;     v[0] *= rstd * g0.x; v[1] *= rstd * g0.y; v[2] *= rstd * g0.z; v[3] *= rstd * g0.w; v[4] *= rstd * g1.x; v[5] *= rstd * g1.y; v[6] *= rstd * g1.z; v[7] *= rstd * g1.w;
;     float pr[8];
; #pragma unroll
;     for (int i = 0; i < 8; ++i) pr[i] = __shfl_xor(v[i], 1);
;     if (sub < 2) {
;         const f32x4 c0 = *(const f32x4*)(tabrow), c1 = *(const f32x4*)(tabrow + 4), s0 = *(const f32x4*)(tabrow + 8), s1 = *(const f32x4*)(tabrow + 12);
;         const float cs[8] = {c0.x, c0.y, c0.z, c0.w, c1.x, c1.y, c1.z, c1.w}, sn[8] = {s0.x, s0.y, s0.z, s0.w, s1.x, s1.y, s1.z, s1.w};
;         const float sg = (sub == 0) ? -1.0f : 1.0f;
; #pragma unroll
;         for (int i = 0; i < 8; ++i) v[i] = v[i] * cs[i] + sg * pr[i] * sn[i];
;     }
; }
	v_and_b32_e32 v57, 0xffff0000, v52
	v_cndmask_b32_e32 v56, v213, v215, vcc
	v_lshlrev_b32_e32 v116, 2, v56
	v_lshlrev_b32_e32 v56, 16, v52
	v_pk_mul_f32 v[58:59], v[56:57], v[56:57]
	v_lshlrev_b32_e32 v52, 16, v53
	v_and_b32_e32 v53, 0xffff0000, v53
	v_pk_mul_f32 v[114:115], v[52:53], v[52:53]
	v_add_f32_e32 v58, v58, v59
	v_lshlrev_b32_e32 v120, 16, v54
	v_and_b32_e32 v121, 0xffff0000, v54
	v_add_f32_e32 v58, v114, v58
	v_pk_mul_f32 v[118:119], v[120:121], v[120:121]
	v_add_f32_e32 v58, v115, v58
	v_lshlrev_b32_e32 v54, 16, v55
	v_and_b32_e32 v55, 0xffff0000, v55
	v_add_f32_e32 v58, v118, v58
	v_pk_mul_f32 v[122:123], v[54:55], v[54:55]
	v_add_f32_e32 v58, v119, v58
	v_add_f32_e32 v58, v122, v58
	v_add_f32_e32 v58, v123, v58
	ds_bpermute_b32 v59, v116, v58
	v_cmp_lt_i32_e32 vcc, v216, v214
	s_waitcnt lgkmcnt(0)
	v_add_f32_e32 v58, v58, v59
	v_cndmask_b32_e32 v63, v213, v216, vcc
	v_lshlrev_b32_e32 v117, 2, v63
	ds_bpermute_b32 v59, v117, v58
	v_cmp_lt_i32_e32 vcc, v217, v214
	s_waitcnt lgkmcnt(0)
	v_add_f32_e32 v58, v58, v59
	v_cndmask_b32_e32 v63, v213, v217, vcc
	v_lshlrev_b32_e32 v118, 2, v63
	v_mov_b32_dpp v59, v58 row_half_mirror row_mask:0xf bank_mask:0xf
	s_waitcnt lgkmcnt(0)
	v_add_f32_e32 v58, v58, v59
	v_fmamk_f32 v58, v58, 0x3c800000, v209
	v_mul_f32_e32 v59, 0x4b800000, v58
	v_cmp_gt_f32_e32 vcc, s96, v58
	s_nop 1
	v_cndmask_b32_e32 v58, v58, v59, vcc
	v_rsq_f32_e32 v58, v58
	s_nop 0
	v_mul_f32_e32 v59, 0x45800000, v58
	v_cndmask_b32_e32 v114, v58, v59, vcc
	s_waitcnt vmcnt(4)
	v_pk_mul_f32 v[58:59], v[44:45], v[114:115] op_sel_hi:[1,0]
	v_cmp_eq_u32_e32 vcc, 0, v61
	v_pk_mul_f32 v[56:57], v[58:59], v[56:57]
	v_pk_mul_f32 v[58:59], v[46:47], v[114:115] op_sel_hi:[1,0]
	s_nop 1
	v_mov_b32_dpp v123, v57 quad_perm:[1,0,3,2] row_mask:0xf bank_mask:0xf
	v_pk_mul_f32 v[58:59], v[58:59], v[52:53]
	v_pk_mul_f32 v[52:53], v[40:41], v[114:115] op_sel_hi:[1,0]
	v_pk_mul_f32 v[114:115], v[42:43], v[114:115] op_sel_hi:[1,0]
	v_pk_mul_f32 v[52:53], v[52:53], v[120:121]
	v_pk_mul_f32 v[54:55], v[114:115], v[54:55]
	v_mov_b32_dpp v121, v56 quad_perm:[1,0,3,2] row_mask:0xf bank_mask:0xf
	v_mov_b32_dpp v119, v58 quad_perm:[1,0,3,2] row_mask:0xf bank_mask:0xf
	v_mov_b32_dpp v122, v59 quad_perm:[1,0,3,2] row_mask:0xf bank_mask:0xf
	v_mov_b32_dpp v115, v52 quad_perm:[1,0,3,2] row_mask:0xf bank_mask:0xf
	v_mov_b32_dpp v120, v53 quad_perm:[1,0,3,2] row_mask:0xf bank_mask:0xf
	v_mov_b32_dpp v63, v54 quad_perm:[1,0,3,2] row_mask:0xf bank_mask:0xf
	v_mov_b32_dpp v114, v55 quad_perm:[1,0,3,2] row_mask:0xf bank_mask:0xf
	s_and_saveexec_b64 s[8:9], s[0:1]
	s_cbranch_execz .LBB0_461
	v_lshlrev_b64 v[136:137], 6, v[172:173]
	v_lshl_add_u64 v[148:149], s[48:49], 0, v[136:137]
	global_load_dwordx4 v[136:139], v[148:149], off offset:32
	global_load_dwordx4 v[140:143], v[148:149], off offset:48
	global_load_dwordx4 v[144:147], v[148:149], off offset:16
	s_nop 0
	global_load_dwordx4 v[148:151], v[148:149], off
	s_waitcnt lgkmcnt(7)
	v_cndmask_b32_e64 v153, v123, -v123, vcc
	s_waitcnt lgkmcnt(4)
	v_cndmask_b32_e64 v123, v122, -v122, vcc
	v_cndmask_b32_e64 v122, v119, -v119, vcc
	s_waitcnt lgkmcnt(1)
	v_cndmask_b32_e64 v63, v63, -v63, vcc
	v_cndmask_b32_e64 v152, v121, -v121, vcc
	v_cndmask_b32_e64 v121, v120, -v120, vcc
	v_cndmask_b32_e64 v120, v115, -v115, vcc
	s_waitcnt lgkmcnt(0)
	v_cndmask_b32_e64 v115, v114, -v114, vcc
	v_mov_b32_e32 v114, v55
	s_waitcnt vmcnt(3)
	v_pk_mul_f32 v[122:123], v[122:123], v[138:139]
	s_waitcnt vmcnt(2)
	v_mul_f32_e32 v138, v63, v142
	s_waitcnt vmcnt(1)
	v_mov_b32_e32 v142, v147
	v_pk_mul_f32 v[114:115], v[114:115], v[142:143]
	v_pk_mul_f32 v[136:137], v[152:153], v[136:137]
	v_pk_mul_f32 v[120:121], v[120:121], v[140:141]
	v_mul_f32_e32 v54, v54, v146
	v_mov_b32_e32 v55, v114
	v_mov_b32_e32 v139, v115
	s_waitcnt vmcnt(0)
	v_pk_fma_f32 v[56:57], v[56:57], v[148:149], v[136:137]
	v_pk_fma_f32 v[58:59], v[58:59], v[150:151], v[122:123]
	v_pk_fma_f32 v[52:53], v[52:53], v[144:145], v[120:121]
	v_pk_add_f32 v[54:55], v[54:55], v[138:139]

; __device__ __forceinline__ void normrope8(float (&v)[8], int sub, const float* gain, const float* tabrow) {
;     float ss = 0.f;
; #pragma unroll
;     for (int i = 0; i < 8; ++i) ss += v[i] * v[i];
;     ss += __shfl_xor(ss, 1); ss += __shfl_xor(ss, 2); ss += __shfl_xor(ss, 4);
;     const float rstd = rsqrtf(ss * (1.0f / 64.0f) + EPS);
;     const f32x4 g0 = *(const f32x4*)(gain + sub * 8), g1 = *(const f32x4*)(gain + sub * 8 + 4);
;     v[0] *= rstd * g0.x; v[1] *= rstd * g0.y; v[2] *= rstd * g0.z; v[3] *= rstd * g0.w; v[4] *= rstd * g1.x; v[5] *= rstd * g1.y; v[6] *= rstd * g1.z; v[7] *= rstd * g1.w;
;     float pr[8];
; #pragma unroll
;     for (int i = 0; i < 8; ++i) pr[i] = __shfl_xor(v[i], 1);
;     if (sub < 2) {
;         const f32x4 c0 = *(const f32x4*)(tabrow), c1 = *(const f32x4*)(tabrow + 4), s0 = *(const f32x4*)(tabrow + 8), s1 = *(const f32x4*)(tabrow + 12);
;         const float cs[8] = {c0.x, c0.y, c0.z, c0.w, c1.x, c1.y, c1.z, c1.w}, sn[8] = {s0.x, s0.y, s0.z, s0.w, s1.x, s1.y, s1.z, s1.w};
;         const float sg = (sub == 0) ? -1.0f : 1.0f;
; #pragma unroll
;         for (int i = 0; i < 8; ++i) v[i] = v[i] * cs[i] + sg * pr[i] * sn[i];
;     }
; }
.LBB0_463:
	s_or_b64 exec, exec, s[4:5]
	v_lshlrev_b32_e32 v48, 16, v36
	v_and_b32_e32 v49, 0xffff0000, v36
	v_lshlrev_b32_e32 v36, 16, v37
	v_and_b32_e32 v37, 0xffff0000, v37
	v_pk_mul_f32 v[52:53], v[48:49], v[48:49]
	v_pk_mul_f32 v[54:55], v[36:37], v[36:37]
	v_add_f32_e32 v52, v52, v53
	v_lshlrev_b32_e32 v50, 16, v38
	v_and_b32_e32 v51, 0xffff0000, v38
	v_add_f32_e32 v52, v54, v52
	v_pk_mul_f32 v[56:57], v[50:51], v[50:51]
	v_add_f32_e32 v52, v55, v52
	v_lshlrev_b32_e32 v38, 16, v39
	v_and_b32_e32 v39, 0xffff0000, v39
	v_add_f32_e32 v52, v56, v52
	v_pk_mul_f32 v[58:59], v[38:39], v[38:39]
	v_add_f32_e32 v52, v57, v52
	v_add_f32_e32 v52, v58, v52
	v_add_f32_e32 v52, v59, v52
	s_nop 1
	v_mov_b32_dpp v53, v52 quad_perm:[1,0,3,2] row_mask:0xf bank_mask:0xf
	s_waitcnt lgkmcnt(0)
	v_add_f32_e32 v52, v52, v53
	s_nop 1
	v_mov_b32_dpp v53, v52 quad_perm:[2,3,0,1] row_mask:0xf bank_mask:0xf
	s_waitcnt lgkmcnt(0)
	v_add_f32_e32 v52, v52, v53
	s_nop 1
	v_mov_b32_dpp v53, v52 row_half_mirror row_mask:0xf bank_mask:0xf
	s_waitcnt lgkmcnt(0)
	v_add_f32_e32 v52, v52, v53
	v_fmamk_f32 v52, v52, 0x3c800000, v209
	v_mul_f32_e32 v53, 0x4b800000, v52
	v_cmp_gt_f32_e64 s[4:5], s96, v52
	s_nop 1
	v_cndmask_b32_e64 v52, v52, v53, s[4:5]
	v_rsq_f32_e32 v52, v52
	s_nop 0
	v_mul_f32_e32 v53, 0x45800000, v52
	v_cndmask_b32_e64 v52, v52, v53, s[4:5]
	s_waitcnt vmcnt(1)
	v_pk_mul_f32 v[46:47], v[46:47], v[52:53] op_sel_hi:[1,0]
	s_waitcnt vmcnt(0)
	v_pk_mul_f32 v[40:41], v[40:41], v[52:53] op_sel_hi:[1,0]
	v_pk_mul_f32 v[44:45], v[44:45], v[52:53] op_sel_hi:[1,0]
	v_pk_mul_f32 v[46:47], v[46:47], v[36:37]
	v_pk_mul_f32 v[36:37], v[40:41], v[50:51]
	v_pk_mul_f32 v[40:41], v[42:43], v[52:53] op_sel_hi:[1,0]
	v_pk_mul_f32 v[44:45], v[44:45], v[48:49]
	v_pk_mul_f32 v[38:39], v[40:41], v[38:39]
	s_nop 1
	v_mov_b32_dpp v50, v44 quad_perm:[1,0,3,2] row_mask:0xf bank_mask:0xf
	v_mov_b32_dpp v52, v45 quad_perm:[1,0,3,2] row_mask:0xf bank_mask:0xf
	v_mov_b32_dpp v43, v46 quad_perm:[1,0,3,2] row_mask:0xf bank_mask:0xf
	v_mov_b32_dpp v51, v47 quad_perm:[1,0,3,2] row_mask:0xf bank_mask:0xf
	v_mov_b32_dpp v42, v36 quad_perm:[1,0,3,2] row_mask:0xf bank_mask:0xf
	v_mov_b32_dpp v49, v37 quad_perm:[1,0,3,2] row_mask:0xf bank_mask:0xf
	v_mov_b32_dpp v40, v38 quad_perm:[1,0,3,2] row_mask:0xf bank_mask:0xf
	v_mov_b32_dpp v41, v39 quad_perm:[1,0,3,2] row_mask:0xf bank_mask:0xf
	v_add_u32_e32 v48, 64, v60
	s_and_saveexec_b64 s[4:5], s[0:1]
	s_cbranch_execz .LBB0_465
	v_add_u32_e32 v53, s13, v48
	v_max_i32_e32 v172, 0, v53
	v_lshlrev_b64 v[54:55], 6, v[172:173]
	v_lshl_add_u64 v[58:59], s[48:49], 0, v[54:55]
	global_load_dwordx4 v[54:57], v[58:59], off offset:32
	global_load_dwordx4 v[136:139], v[58:59], off offset:48
	global_load_dwordx4 v[140:143], v[58:59], off offset:16
	global_load_dwordx4 v[144:147], v[58:59], off
	s_waitcnt lgkmcnt(6)
	v_cndmask_b32_e64 v53, v52, -v52, vcc
	v_cndmask_b32_e64 v52, v50, -v50, vcc
	s_waitcnt lgkmcnt(5)
	v_cndmask_b32_e64 v50, v43, -v43, vcc
	s_waitcnt lgkmcnt(2)
	v_cndmask_b32_e64 v43, v49, -v49, vcc
	s_waitcnt lgkmcnt(1)
	v_cndmask_b32_e64 v49, v40, -v40, vcc
	s_waitcnt lgkmcnt(0)
	v_cndmask_b32_e64 v41, v41, -v41, vcc
	v_mov_b32_e32 v40, v39
	v_cndmask_b32_e64 v51, v51, -v51, vcc
	v_cndmask_b32_e64 v42, v42, -v42, vcc
	s_waitcnt vmcnt(3)
	v_pk_mul_f32 v[52:53], v[52:53], v[54:55]
	s_waitcnt vmcnt(2)
	v_mul_f32_e32 v54, v49, v138
	s_waitcnt vmcnt(1)
	v_mov_b32_e32 v138, v143
	v_pk_mul_f32 v[40:41], v[40:41], v[138:139]
	v_pk_mul_f32 v[50:51], v[50:51], v[56:57]
	v_pk_mul_f32 v[42:43], v[42:43], v[136:137]
	v_mul_f32_e32 v38, v38, v142
	v_mov_b32_e32 v39, v40
	v_mov_b32_e32 v55, v41
	s_waitcnt vmcnt(0)
	v_pk_fma_f32 v[44:45], v[44:45], v[144:145], v[52:53]
	v_pk_fma_f32 v[46:47], v[46:47], v[146:147], v[50:51]
	v_pk_fma_f32 v[36:37], v[36:37], v[140:141], v[42:43]
	v_pk_add_f32 v[38:39], v[38:39], v[54:55]

; __device__ __forceinline__ void normrope8(float (&v)[8], int sub, const float* gain, const float* tabrow) {
;     float ss = 0.f;
; #pragma unroll
;     for (int i = 0; i < 8; ++i) ss += v[i] * v[i];
;     ss += __shfl_xor(ss, 1); ss += __shfl_xor(ss, 2); ss += __shfl_xor(ss, 4);
;     const float rstd = rsqrtf(ss * (1.0f / 64.0f) + EPS);
;     const f32x4 g0 = *(const f32x4*)(gain + sub * 8), g1 = *(const f32x4*)(gain + sub * 8 + 4);
;     v[0] *= rstd * g0.x; v[1] *= rstd * g0.y; v[2] *= rstd * g0.z; v[3] *= rstd * g0.w; v[4] *= rstd * g1.x; v[5] *= rstd * g1.y; v[6] *= rstd * g1.z; v[7] *= rstd * g1.w;
;     float pr[8];
; #pragma unroll
;     for (int i = 0; i < 8; ++i) pr[i] = __shfl_xor(v[i], 1);
;     if (sub < 2) {
;         const f32x4 c0 = *(const f32x4*)(tabrow), c1 = *(const f32x4*)(tabrow + 4), s0 = *(const f32x4*)(tabrow + 8), s1 = *(const f32x4*)(tabrow + 12);
;         const float cs[8] = {c0.x, c0.y, c0.z, c0.w, c1.x, c1.y, c1.z, c1.w}, sn[8] = {s0.x, s0.y, s0.z, s0.w, s1.x, s1.y, s1.z, s1.w};
;         const float sg = (sub == 0) ? -1.0f : 1.0f;
; #pragma unroll
;         for (int i = 0; i < 8; ++i) v[i] = v[i] * cs[i] + sg * pr[i] * sn[i];
;     }
; }
.LBB0_467:
	s_or_b64 exec, exec, s[4:5]
	v_lshlrev_b32_e32 v36, 16, v32
	v_and_b32_e32 v37, 0xffff0000, v32
	v_lshlrev_b32_e32 v38, 16, v33
	v_and_b32_e32 v39, 0xffff0000, v33
	v_lshlrev_b32_e32 v40, 16, v34
	v_and_b32_e32 v41, 0xffff0000, v34
	v_lshlrev_b32_e32 v42, 16, v35
	v_and_b32_e32 v43, 0xffff0000, v35
	global_load_dwordx4 v[28:31], v[114:115], off offset:16
	global_load_dwordx4 v[32:35], v[114:115], off
	v_pk_mul_f32 v[44:45], v[36:37], v[36:37]
	v_pk_mul_f32 v[46:47], v[38:39], v[38:39]
	v_add_f32_e32 v44, v44, v45
	v_add_f32_e32 v44, v46, v44
	v_pk_mul_f32 v[50:51], v[40:41], v[40:41]
	v_add_f32_e32 v44, v47, v44
	v_add_f32_e32 v44, v50, v44
	v_pk_mul_f32 v[52:53], v[42:43], v[42:43]
	v_add_f32_e32 v44, v51, v44
	v_add_f32_e32 v44, v52, v44
	v_add_f32_e32 v44, v53, v44
	s_nop 1
	v_mov_b32_dpp v45, v44 quad_perm:[1,0,3,2] row_mask:0xf bank_mask:0xf
	s_waitcnt lgkmcnt(0)
	v_add_f32_e32 v44, v44, v45
	s_nop 1
	v_mov_b32_dpp v45, v44 quad_perm:[2,3,0,1] row_mask:0xf bank_mask:0xf
	s_waitcnt lgkmcnt(0)
	v_add_f32_e32 v44, v44, v45
	s_nop 1
	v_mov_b32_dpp v45, v44 row_half_mirror row_mask:0xf bank_mask:0xf
	s_waitcnt lgkmcnt(0)
	v_add_f32_e32 v44, v44, v45
	v_fmamk_f32 v44, v44, 0x3c800000, v209
	v_cmp_gt_f32_e64 s[4:5], s96, v44
	v_mul_f32_e32 v45, 0x4b800000, v44
	s_nop 0
	v_cndmask_b32_e64 v44, v44, v45, s[4:5]
	v_rsq_f32_e32 v44, v44
	s_nop 0
	v_mul_f32_e32 v45, 0x45800000, v44
	v_cndmask_b32_e64 v44, v44, v45, s[4:5]
	s_waitcnt vmcnt(0)
	v_pk_mul_f32 v[46:47], v[32:33], v[44:45] op_sel_hi:[1,0]
	s_nop 0
	v_pk_mul_f32 v[36:37], v[46:47], v[36:37]
	v_pk_mul_f32 v[46:47], v[34:35], v[44:45] op_sel_hi:[1,0]
	s_nop 1
	v_mov_b32_dpp v50, v36 quad_perm:[1,0,3,2] row_mask:0xf bank_mask:0xf
	v_pk_mul_f32 v[38:39], v[46:47], v[38:39]
	v_pk_mul_f32 v[46:47], v[28:29], v[44:45] op_sel_hi:[1,0]
	v_pk_mul_f32 v[44:45], v[30:31], v[44:45] op_sel_hi:[1,0]
	v_pk_mul_f32 v[40:41], v[46:47], v[40:41]
	v_pk_mul_f32 v[42:43], v[44:45], v[42:43]
	v_mov_b32_dpp v52, v37 quad_perm:[1,0,3,2] row_mask:0xf bank_mask:0xf
	v_mov_b32_dpp v47, v38 quad_perm:[1,0,3,2] row_mask:0xf bank_mask:0xf
	v_mov_b32_dpp v51, v39 quad_perm:[1,0,3,2] row_mask:0xf bank_mask:0xf
	v_mov_b32_dpp v46, v40 quad_perm:[1,0,3,2] row_mask:0xf bank_mask:0xf
	v_mov_b32_dpp v49, v41 quad_perm:[1,0,3,2] row_mask:0xf bank_mask:0xf
	v_mov_b32_dpp v44, v42 quad_perm:[1,0,3,2] row_mask:0xf bank_mask:0xf
	v_mov_b32_dpp v45, v43 quad_perm:[1,0,3,2] row_mask:0xf bank_mask:0xf
	s_and_saveexec_b64 s[4:5], s[0:1]
	s_cbranch_execz .LBB0_469
	v_lshlrev_b64 v[54:55], 6, v[112:113]
	v_lshl_add_u64 v[58:59], s[48:49], 0, v[54:55]
	global_load_dwordx4 v[54:57], v[58:59], off offset:32
	global_load_dwordx4 v[136:139], v[58:59], off offset:48
	global_load_dwordx4 v[140:143], v[58:59], off offset:16
	global_load_dwordx4 v[144:147], v[58:59], off
	s_waitcnt lgkmcnt(6)
	v_cndmask_b32_e64 v53, v52, -v52, vcc
	v_cndmask_b32_e64 v52, v50, -v50, vcc
	s_waitcnt lgkmcnt(5)
	v_cndmask_b32_e64 v50, v47, -v47, vcc
	s_waitcnt lgkmcnt(2)
	v_cndmask_b32_e64 v47, v49, -v49, vcc
	s_waitcnt lgkmcnt(1)
	v_cndmask_b32_e64 v49, v44, -v44, vcc
	s_waitcnt lgkmcnt(0)
	v_cndmask_b32_e64 v45, v45, -v45, vcc
	v_mov_b32_e32 v44, v43
	v_cndmask_b32_e64 v51, v51, -v51, vcc
	v_cndmask_b32_e64 v46, v46, -v46, vcc
	s_waitcnt vmcnt(3)
	v_pk_mul_f32 v[52:53], v[52:53], v[54:55]
	s_waitcnt vmcnt(2)
	v_mul_f32_e32 v54, v49, v138
	s_waitcnt vmcnt(1)
	v_mov_b32_e32 v138, v143
	v_pk_mul_f32 v[44:45], v[44:45], v[138:139]
	v_pk_mul_f32 v[50:51], v[50:51], v[56:57]
	v_pk_mul_f32 v[46:47], v[46:47], v[136:137]
	v_mul_f32_e32 v42, v42, v142
	v_mov_b32_e32 v43, v44
	v_mov_b32_e32 v55, v45
	s_waitcnt vmcnt(0)
	v_pk_fma_f32 v[36:37], v[36:37], v[144:145], v[52:53]
	v_pk_fma_f32 v[38:39], v[38:39], v[146:147], v[50:51]
	v_pk_fma_f32 v[40:41], v[40:41], v[140:141], v[46:47]
	v_pk_add_f32 v[42:43], v[42:43], v[54:55]

; #define LAS __attribute__((address_space(3)))
; __device__ __forceinline__ u32x4 pack8(const float (&f)[8]) { u32x4 w; w.x = pk_bf16(f[0], f[1]); w.y = pk_bf16(f[2], f[3]); w.z = pk_bf16(f[4], f[5]); w.w = pk_bf16(f[6], f[7]); return w; }
; __device__ __forceinline__ void normrope8(float (&v)[8], int sub, const float* gain, const float* tabrow) {
;     float ss = 0.f;
; #pragma unroll
;     for (int i = 0; i < 8; ++i) ss += v[i] * v[i];
;     ss += __shfl_xor(ss, 1); ss += __shfl_xor(ss, 2); ss += __shfl_xor(ss, 4);
;     const float rstd = rsqrtf(ss * (1.0f / 64.0f) + EPS);
;     const f32x4 g0 = *(const f32x4*)(gain + sub * 8), g1 = *(const f32x4*)(gain + sub * 8 + 4);
;     v[0] *= rstd * g0.x; v[1] *= rstd * g0.y; v[2] *= rstd * g0.z; v[3] *= rstd * g0.w; v[4] *= rstd * g1.x; v[5] *= rstd * g1.y; v[6] *= rstd * g1.z; v[7] *= rstd * g1.w;
;     float pr[8];
; #pragma unroll
;     for (int i = 0; i < 8; ++i) pr[i] = __shfl_xor(v[i], 1);
;     if (sub < 2) {
;         const f32x4 c0 = *(const f32x4*)(tabrow), c1 = *(const f32x4*)(tabrow + 4), s0 = *(const f32x4*)(tabrow + 8), s1 = *(const f32x4*)(tabrow + 12);
;         const float cs[8] = {c0.x, c0.y, c0.z, c0.w, c1.x, c1.y, c1.z, c1.w}, sn[8] = {s0.x, s0.y, s0.z, s0.w, s1.x, s1.y, s1.z, s1.w};
;         const float sg = (sub == 0) ? -1.0f : 1.0f;
; #pragma unroll
;         for (int i = 0; i < 8; ++i) v[i] = v[i] * cs[i] + sg * pr[i] * sn[i];
;     }
; }
; __device__ __forceinline__ void attn_prompt_item(const Args& a, int l, int item, LAS unsigned char* lds, int tid, int lane, int wave) {
;     ...
;     for (int pass = 0; pass < 4; ++pass) {
;         const int j = pass * 64 + rl; const int pos = 128 * (b - 1) + j; const int posc = pos < 0 ? 0 : pos;
;         const u32x4 kw = kws[pass], vw = vws[pass];
;         float kf[8]; unpack8(kw, kf);
;         normrope8(kf, sub, kg, tab + (size_t)posc * 16);
;         *(LAS u32x4*)(Kl + j * 144 + sub * 16) = pack8(kf);
.LBB0_471:
	s_or_b64 exec, exec, s[4:5]
	v_lshlrev_b32_e32 v24, 16, v20
	v_and_b32_e32 v25, 0xffff0000, v20
	v_lshlrev_b32_e32 v20, 16, v21
	v_and_b32_e32 v21, 0xffff0000, v21
	v_pk_mul_f32 v[26:27], v[24:25], v[24:25]
	v_pk_mul_f32 v[38:39], v[20:21], v[20:21]
	v_add_f32_e32 v26, v26, v27
	v_lshlrev_b32_e32 v36, 16, v22
	v_and_b32_e32 v37, 0xffff0000, v22
	v_add_f32_e32 v26, v38, v26
	v_pk_mul_f32 v[40:41], v[36:37], v[36:37]
	v_add_f32_e32 v26, v39, v26
	v_lshlrev_b32_e32 v22, 16, v23
	v_and_b32_e32 v23, 0xffff0000, v23
	v_add_f32_e32 v26, v40, v26
	v_pk_mul_f32 v[42:43], v[22:23], v[22:23]
	v_add_f32_e32 v26, v41, v26
	v_add_f32_e32 v26, v42, v26
	v_add_f32_e32 v26, v43, v26
	s_nop 1
	v_mov_b32_dpp v27, v26 quad_perm:[1,0,3,2] row_mask:0xf bank_mask:0xf
	s_waitcnt lgkmcnt(0)
	v_add_f32_e32 v26, v26, v27
	s_nop 1
	v_mov_b32_dpp v27, v26 quad_perm:[2,3,0,1] row_mask:0xf bank_mask:0xf
	s_waitcnt lgkmcnt(0)
	v_add_f32_e32 v26, v26, v27
	s_nop 1
	v_mov_b32_dpp v27, v26 row_half_mirror row_mask:0xf bank_mask:0xf
	s_waitcnt lgkmcnt(0)
	v_add_f32_e32 v26, v26, v27
	v_fmamk_f32 v26, v26, 0x3c800000, v209
	v_mul_f32_e32 v27, 0x4b800000, v26
	v_cmp_gt_f32_e64 s[4:5], s96, v26
	s_nop 1
	v_cndmask_b32_e64 v26, v26, v27, s[4:5]
	v_rsq_f32_e32 v26, v26
	s_nop 0
	v_mul_f32_e32 v27, 0x45800000, v26
	v_cndmask_b32_e64 v38, v26, v27, s[4:5]
	s_waitcnt vmcnt(1)
	v_pk_mul_f32 v[26:27], v[32:33], v[38:39] op_sel_hi:[1,0]
	v_pk_mul_f32 v[32:33], v[34:35], v[38:39] op_sel_hi:[1,0]
	s_waitcnt vmcnt(0)
	v_pk_mul_f32 v[28:29], v[28:29], v[38:39] op_sel_hi:[1,0]
	v_pk_mul_f32 v[24:25], v[26:27], v[24:25]
	v_pk_mul_f32 v[26:27], v[32:33], v[20:21]
	v_pk_mul_f32 v[20:21], v[28:29], v[36:37]
	v_pk_mul_f32 v[28:29], v[30:31], v[38:39] op_sel_hi:[1,0]
	v_mov_b32_dpp v34, v24 quad_perm:[1,0,3,2] row_mask:0xf bank_mask:0xf
	v_pk_mul_f32 v[22:23], v[28:29], v[22:23]
	v_mov_b32_dpp v36, v25 quad_perm:[1,0,3,2] row_mask:0xf bank_mask:0xf
	v_mov_b32_dpp v32, v26 quad_perm:[1,0,3,2] row_mask:0xf bank_mask:0xf
	v_mov_b32_dpp v35, v27 quad_perm:[1,0,3,2] row_mask:0xf bank_mask:0xf
	v_mov_b32_dpp v31, v20 quad_perm:[1,0,3,2] row_mask:0xf bank_mask:0xf
	v_mov_b32_dpp v33, v21 quad_perm:[1,0,3,2] row_mask:0xf bank_mask:0xf
	v_mov_b32_dpp v29, v22 quad_perm:[1,0,3,2] row_mask:0xf bank_mask:0xf
	v_mov_b32_dpp v30, v23 quad_perm:[1,0,3,2] row_mask:0xf bank_mask:0xf
	v_add_u32_e32 v28, 0xc0, v60
	s_and_saveexec_b64 s[4:5], s[0:1]
	s_cbranch_execz .LBB0_473
	v_add_u32_e32 v37, s13, v28
	v_max_i32_e32 v172, 0, v37
	v_lshlrev_b64 v[38:39], 6, v[172:173]
	v_lshl_add_u64 v[46:47], s[48:49], 0, v[38:39]
	global_load_dwordx4 v[38:41], v[46:47], off offset:32
	global_load_dwordx4 v[42:45], v[46:47], off offset:48
	global_load_dwordx4 v[50:53], v[46:47], off offset:16
	global_load_dwordx4 v[54:57], v[46:47], off
	s_waitcnt lgkmcnt(6)
	v_cndmask_b32_e64 v37, v36, -v36, vcc
	v_cndmask_b32_e64 v36, v34, -v34, vcc
	s_waitcnt lgkmcnt(1)
	v_cndmask_b32_e64 v29, v29, -v29, vcc
	v_cndmask_b32_e64 v34, v32, -v32, vcc
	v_cndmask_b32_e64 v32, v31, -v31, vcc
	s_waitcnt lgkmcnt(0)
	v_cndmask_b32_e64 v31, v30, -v30, vcc
	v_mov_b32_e32 v30, v23
	v_cndmask_b32_e64 v35, v35, -v35, vcc
	v_cndmask_b32_e64 v33, v33, -v33, vcc
	s_waitcnt vmcnt(3)
	v_pk_mul_f32 v[36:37], v[36:37], v[38:39]
	s_waitcnt vmcnt(2)
	v_mul_f32_e32 v38, v29, v44
	s_waitcnt vmcnt(1)
	v_mov_b32_e32 v44, v53
	v_pk_mul_f32 v[30:31], v[30:31], v[44:45]
	v_pk_mul_f32 v[34:35], v[34:35], v[40:41]
	v_pk_mul_f32 v[32:33], v[32:33], v[42:43]
	v_mul_f32_e32 v22, v22, v52
	v_mov_b32_e32 v23, v30
	v_mov_b32_e32 v39, v31
	s_waitcnt vmcnt(0)
	v_pk_fma_f32 v[24:25], v[24:25], v[54:55], v[36:37]
	v_pk_fma_f32 v[26:27], v[26:27], v[56:57], v[34:35]
	v_pk_fma_f32 v[20:21], v[20:21], v[50:51], v[32:33]
	v_pk_add_f32 v[22:23], v[22:23], v[38:39]
